# up-GEMM conv epilogue general path: conv-bias loads of both column halves issued together (16 sites), halving serialized round trips on sequence-boundary tiles
# speedup vs baseline: 1.0056x; 1.0056x over previous
.LBB0_1198:
	ds_read_b32 v110, v223
	s_waitcnt lgkmcnt(0)
	v_mov_b32_dpp v72, v58 row_shr:1 row_mask:0xf bank_mask:0xf
	v_mov_b32_dpp v73, v59 row_shr:1 row_mask:0xf bank_mask:0xf
	v_mov_b32_dpp v76, v50 row_shr:1 row_mask:0xf bank_mask:0xf
	v_mov_b32_dpp v77, v51 row_shr:1 row_mask:0xf bank_mask:0xf
	v_and_b32_e32 v70, 15, v110
	v_mul_u32_u24_e32 v70, 0x1600, v70
	v_lshlrev_b32_e32 v146, 2, v70
	v_lshl_add_u64 v[70:71], s[68:69], 0, v[146:147]
	v_lshl_add_u64 v[88:89], v[70:71], 0, v[114:115]
	v_and_b32_e32 v71, 16, v110
	v_cmp_eq_u32_e32 vcc, 0, v71
	v_and_b32_e32 v71, 32, v110
	global_load_dwordx4 v[110:113], v[88:89], off
	global_load_dwordx4 v[252:255], v[88:89], off offset:512
	v_cmp_eq_u32_e64 s[0:1], 0, v71
	v_cndmask_b32_e64 v116, v66, 0, vcc
	v_cndmask_b32_e64 v117, v67, 0, vcc
	v_cndmask_b32_e64 v118, v68, 0, vcc
	v_cndmask_b32_e64 v119, v69, 0, vcc
	v_cndmask_b32_e64 v84, v84, 0, s[0:1]
	v_cndmask_b32_e64 v85, v85, 0, s[0:1]
	v_cndmask_b32_e64 v86, v86, 0, s[0:1]
	v_cndmask_b32_e64 v87, v87, 0, s[0:1]
	v_cndmask_b32_e64 v76, v76, 0, s[0:1]
	v_cndmask_b32_e64 v77, v77, 0, s[0:1]
	v_mov_b32_dpp v74, v60 row_shr:1 row_mask:0xf bank_mask:0xf
	v_mov_b32_dpp v75, v61 row_shr:1 row_mask:0xf bank_mask:0xf
	v_mov_b32_dpp v78, v52 row_shr:1 row_mask:0xf bank_mask:0xf
	v_mov_b32_dpp v79, v53 row_shr:1 row_mask:0xf bank_mask:0xf
	v_cndmask_b32_e64 v78, v78, 0, s[0:1]
	v_cndmask_b32_e64 v79, v79, 0, s[0:1]
	v_mov_b32_e32 v70, 0
	s_waitcnt vmcnt(0)
	v_pk_fma_f32 v[112:113], v[212:213], v[108:109], v[112:113]
	v_pk_fma_f32 v[110:111], v[210:211], v[106:107], v[110:111]
	v_pk_fma_f32 v[112:113], v[104:105], v[118:119], v[112:113]
	v_pk_fma_f32 v[110:111], v[102:103], v[116:117], v[110:111]
	v_pk_fma_f32 v[112:113], v[100:101], v[86:87], v[112:113]
	v_pk_fma_f32 v[110:111], v[98:99], v[84:85], v[110:111]
	v_mov_b64_e32 v[84:85], v[252:253]
	v_mov_b64_e32 v[86:87], v[254:255]
	v_mul_f32_e32 v71, 0xbfb8aa3b, v110
	v_exp_f32_e32 v71, v71
	v_cndmask_b32_e64 v88, v72, 0, vcc
	v_cndmask_b32_e64 v89, v73, 0, vcc
	v_cndmask_b32_e64 v116, v74, 0, vcc
	v_add_f32_e32 v71, 1.0, v71
	v_rcp_f32_e32 v71, v71
	v_cndmask_b32_e64 v117, v75, 0, vcc
	v_mul_f32_e32 v71, v110, v71
	s_waitcnt vmcnt(0)
	v_pk_fma_f32 v[84:85], v[214:215], v[94:95], v[84:85]
	s_nop 0
	v_pk_fma_f32 v[84:85], v[90:91], v[88:89], v[84:85]
	v_pk_fma_f32 v[86:87], v[216:217], v[96:97], v[86:87]
	v_pk_fma_f32 v[76:77], v[80:81], v[76:77], v[84:85]
	v_pk_fma_f32 v[86:87], v[92:93], v[116:117], v[86:87]
	v_mul_f32_e32 v71, v76, v71
	v_mul_f32_e32 v76, 0xbfb8aa3b, v111
	v_exp_f32_e32 v76, v76
	v_pk_fma_f32 v[78:79], v[82:83], v[78:79], v[86:87]
	v_add_f32_e32 v76, 1.0, v76
	v_rcp_f32_e32 v76, v76
	s_nop 0
	v_mul_f32_e32 v76, v111, v76
	v_mul_f32_e32 v76, v77, v76
	v_mul_f32_e32 v77, 0xbfb8aa3b, v112
	v_exp_f32_e32 v77, v77
	v_cvt_pk_bf16_f32 v84, v71, v76
	ds_read_b32 v71, v225
	v_add_f32_e32 v77, 1.0, v77
	v_rcp_f32_e32 v77, v77
	s_waitcnt lgkmcnt(0)
	v_and_b32_e32 v76, 15, v71
	v_mul_u32_u24_e32 v76, 0x1600, v76
	v_mul_f32_e32 v77, v112, v77
	v_mul_f32_e32 v77, v78, v77
	v_mul_f32_e32 v78, 0xbfb8aa3b, v113
	v_exp_f32_e32 v78, v78
	v_lshlrev_b32_e32 v146, 2, v76
	v_add_f32_e32 v78, 1.0, v78
	v_rcp_f32_e32 v78, v78
	s_nop 0
	v_mul_f32_e32 v78, v113, v78
	v_mul_f32_e32 v78, v79, v78
	v_cvt_pk_bf16_f32 v85, v77, v78
	v_lshl_add_u64 v[76:77], s[68:69], 0, v[146:147]
	v_lshl_add_u64 v[86:87], v[76:77], 0, v[114:115]
	v_and_b32_e32 v76, 16, v71
	v_cmp_eq_u32_e32 vcc, 0, v76
	global_load_dwordx4 v[76:79], v[86:87], off
	global_load_dwordx4 v[252:255], v[86:87], off offset:512
	v_and_b32_e32 v71, 32, v71
	v_cmp_eq_u32_e64 s[0:1], 0, v71
	v_cndmask_b32_e64 v88, v210, 0, vcc
	v_cndmask_b32_e64 v89, v211, 0, vcc
	v_cndmask_b32_e64 v110, v212, 0, vcc
	v_cndmask_b32_e64 v111, v213, 0, vcc
	v_cndmask_b32_e64 v66, v66, 0, s[0:1]
	v_cndmask_b32_e64 v67, v67, 0, s[0:1]
	v_cndmask_b32_e64 v68, v68, 0, s[0:1]
	v_cndmask_b32_e64 v69, v69, 0, s[0:1]
	v_cndmask_b32_e64 v72, v72, 0, s[0:1]
	v_cndmask_b32_e64 v73, v73, 0, s[0:1]
	v_cndmask_b32_e64 v74, v74, 0, s[0:1]
	v_cndmask_b32_e64 v75, v75, 0, s[0:1]
	s_waitcnt vmcnt(0)
	v_pk_fma_f32 v[78:79], v[204:205], v[108:109], v[78:79]
	v_pk_fma_f32 v[76:77], v[202:203], v[106:107], v[76:77]
	v_pk_fma_f32 v[78:79], v[104:105], v[110:111], v[78:79]
	v_pk_fma_f32 v[76:77], v[102:103], v[88:89], v[76:77]
	v_pk_fma_f32 v[78:79], v[100:101], v[68:69], v[78:79]
	v_pk_fma_f32 v[76:77], v[98:99], v[66:67], v[76:77]
	v_mov_b64_e32 v[66:67], v[252:253]
	v_mov_b64_e32 v[68:69], v[254:255]
	v_mul_f32_e32 v71, 0xbfb8aa3b, v76
	v_exp_f32_e32 v71, v71
	v_cndmask_b32_e64 v86, v214, 0, vcc
	v_cndmask_b32_e64 v87, v215, 0, vcc
	v_cndmask_b32_e64 v88, v216, 0, vcc
	v_add_f32_e32 v71, 1.0, v71
	v_rcp_f32_e32 v71, v71
	v_cndmask_b32_e64 v89, v217, 0, vcc
	v_mul_f32_e32 v71, v76, v71
	s_waitcnt vmcnt(0)
	v_pk_fma_f32 v[66:67], v[206:207], v[94:95], v[66:67]
	s_nop 0
	v_pk_fma_f32 v[66:67], v[90:91], v[86:87], v[66:67]
	v_pk_fma_f32 v[68:69], v[208:209], v[96:97], v[68:69]
	v_pk_fma_f32 v[66:67], v[80:81], v[72:73], v[66:67]
	v_pk_fma_f32 v[68:69], v[92:93], v[88:89], v[68:69]
	v_mul_f32_e32 v66, v66, v71
	v_mul_f32_e32 v71, 0xbfb8aa3b, v77
	v_exp_f32_e32 v71, v71
	v_pk_fma_f32 v[68:69], v[82:83], v[74:75], v[68:69]
	v_add_f32_e32 v71, 1.0, v71
	v_rcp_f32_e32 v71, v71
	s_nop 0
	v_mul_f32_e32 v71, v77, v71
	v_mul_f32_e32 v67, v67, v71
	v_mul_f32_e32 v71, 0xbfb8aa3b, v78
	v_exp_f32_e32 v71, v71
	v_cvt_pk_bf16_f32 v74, v66, v67
	s_nop 0
	v_add_f32_e32 v71, 1.0, v71
	v_rcp_f32_e32 v71, v71
	s_nop 0
	v_mul_f32_e32 v71, v78, v71
	v_mul_f32_e32 v68, v68, v71
	v_mul_f32_e32 v71, 0xbfb8aa3b, v79
	v_exp_f32_e32 v71, v71
	s_nop 0
	v_add_f32_e32 v71, 1.0, v71
	v_rcp_f32_e32 v71, v71
	s_nop 0
	v_mul_f32_e32 v71, v79, v71
	v_mul_f32_e32 v69, v69, v71
	v_cvt_pk_bf16_f32 v75, v68, v69
	ds_read_b32 v68, v227
	s_waitcnt lgkmcnt(0)
	v_and_b32_e32 v66, 15, v68
	v_mul_u32_u24_e32 v66, 0x1600, v66
	v_lshlrev_b32_e32 v146, 2, v66
	v_lshl_add_u64 v[66:67], s[68:69], 0, v[146:147]
	v_lshl_add_u64 v[72:73], v[66:67], 0, v[114:115]
	v_and_b32_e32 v66, 16, v68
	v_cmp_eq_u32_e32 vcc, 0, v66
	v_and_b32_e32 v66, 32, v68
	v_cmp_eq_u32_e64 s[0:1], 0, v66
	global_load_dwordx4 v[66:69], v[72:73], off
	global_load_dwordx4 v[252:255], v[72:73], off offset:512
	v_cndmask_b32_e64 v76, v202, 0, vcc
	v_cndmask_b32_e64 v77, v203, 0, vcc
	v_cndmask_b32_e64 v86, v204, 0, vcc
	v_cndmask_b32_e64 v87, v205, 0, vcc
	v_cndmask_b32_e64 v78, v210, 0, s[0:1]
	v_cndmask_b32_e64 v79, v211, 0, s[0:1]
	v_cndmask_b32_e64 v88, v212, 0, s[0:1]
	v_cndmask_b32_e64 v89, v213, 0, s[0:1]
	v_cndmask_b32_e64 v110, v216, 0, s[0:1]
	v_cndmask_b32_e64 v111, v217, 0, s[0:1]
	s_waitcnt vmcnt(0)
	v_pk_fma_f32 v[68:69], v[56:57], v[108:109], v[68:69]
	v_pk_fma_f32 v[66:67], v[54:55], v[106:107], v[66:67]
	v_pk_fma_f32 v[68:69], v[104:105], v[86:87], v[68:69]
	v_pk_fma_f32 v[66:67], v[102:103], v[76:77], v[66:67]
	v_pk_fma_f32 v[76:77], v[100:101], v[88:89], v[68:69]
	v_pk_fma_f32 v[78:79], v[98:99], v[78:79], v[66:67]
	v_mov_b64_e32 v[66:67], v[252:253]
	v_mov_b64_e32 v[68:69], v[254:255]
	v_mul_f32_e32 v71, 0xbfb8aa3b, v78
	v_exp_f32_e32 v71, v71
	v_cndmask_b32_e64 v72, v206, 0, vcc
	v_cndmask_b32_e64 v73, v207, 0, vcc
	v_cndmask_b32_e64 v86, v214, 0, s[0:1]
	v_add_f32_e32 v71, 1.0, v71
	v_rcp_f32_e32 v71, v71
	v_cndmask_b32_e64 v87, v215, 0, s[0:1]
	v_cndmask_b32_e64 v88, v208, 0, vcc
	v_cndmask_b32_e64 v89, v209, 0, vcc
	v_mul_f32_e32 v71, v78, v71
	s_waitcnt vmcnt(0)
	v_pk_fma_f32 v[66:67], v[50:51], v[94:95], v[66:67]
	s_nop 0
	v_pk_fma_f32 v[66:67], v[90:91], v[72:73], v[66:67]
	v_pk_fma_f32 v[68:69], v[52:53], v[96:97], v[68:69]
	v_pk_fma_f32 v[66:67], v[80:81], v[86:87], v[66:67]
	v_pk_fma_f32 v[68:69], v[92:93], v[88:89], v[68:69]
	v_mul_f32_e32 v66, v66, v71
	v_mul_f32_e32 v71, 0xbfb8aa3b, v79
	v_exp_f32_e32 v71, v71
	v_pk_fma_f32 v[68:69], v[82:83], v[110:111], v[68:69]
	v_add_f32_e32 v71, 1.0, v71
	v_rcp_f32_e32 v71, v71
	s_nop 0
	v_mul_f32_e32 v71, v79, v71
	v_mul_f32_e32 v67, v67, v71
	v_mul_f32_e32 v71, 0xbfb8aa3b, v76
	v_exp_f32_e32 v71, v71
	s_nop 0
	v_add_f32_e32 v71, 1.0, v71
	v_rcp_f32_e32 v71, v71
	s_nop 0
	v_mul_f32_e32 v71, v76, v71
	v_mul_f32_e32 v71, v68, v71
	v_mul_f32_e32 v68, 0xbfb8aa3b, v77
	v_exp_f32_e32 v68, v68
	s_nop 0
	v_add_f32_e32 v68, 1.0, v68
	v_rcp_f32_e32 v68, v68
	s_nop 0
	v_mul_f32_e32 v68, v77, v68
	v_mul_f32_e32 v69, v69, v68
	v_cvt_pk_bf16_f32 v69, v71, v69
	ds_read_b32 v71, v229
	v_cvt_pk_bf16_f32 v68, v66, v67
	s_waitcnt lgkmcnt(0)
	v_and_b32_e32 v66, 15, v71
	v_mul_u32_u24_e32 v66, 0x1600, v66
	v_lshlrev_b32_e32 v146, 2, v66
	v_lshl_add_u64 v[66:67], s[68:69], 0, v[146:147]
	v_lshl_add_u64 v[86:87], v[66:67], 0, v[114:115]
	global_load_dwordx4 v[76:79], v[86:87], off
	global_load_dwordx4 v[252:255], v[86:87], off offset:512
	v_and_b32_e32 v66, 16, v71
	v_cmp_eq_u32_e32 vcc, 0, v66
	v_and_b32_e32 v66, 32, v71
	v_cmp_eq_u32_e64 s[62:63], 0, v66
	v_cndmask_b32_e64 v66, v54, 0, vcc
	v_cndmask_b32_e64 v67, v55, 0, vcc
	v_cndmask_b32_e64 v72, v202, 0, s[62:63]
	v_cndmask_b32_e64 v73, v203, 0, s[62:63]
	v_cndmask_b32_e64 v88, v56, 0, vcc
	v_cndmask_b32_e64 v89, v57, 0, vcc
	v_cndmask_b32_e64 v110, v204, 0, s[62:63]
	v_cndmask_b32_e64 v111, v205, 0, s[62:63]
	v_cndmask_b32_e64 v112, v208, 0, s[62:63]
	v_cndmask_b32_e64 v113, v209, 0, s[62:63]
	s_waitcnt vmcnt(0)
	v_pk_fma_f32 v[76:77], v[62:63], v[106:107], v[76:77]
	v_pk_fma_f32 v[78:79], v[64:65], v[108:109], v[78:79]
	v_pk_fma_f32 v[76:77], v[102:103], v[66:67], v[76:77]
	v_pk_fma_f32 v[66:67], v[104:105], v[88:89], v[78:79]
	v_pk_fma_f32 v[72:73], v[98:99], v[72:73], v[76:77]
	v_mov_b64_e32 v[76:77], v[252:253]
	v_mov_b64_e32 v[78:79], v[254:255]
	v_mul_f32_e32 v71, 0xbfb8aa3b, v72
	v_exp_f32_e32 v71, v71
	v_pk_fma_f32 v[66:67], v[100:101], v[110:111], v[66:67]
	v_cndmask_b32_e64 v110, v52, 0, vcc
	v_cndmask_b32_e64 v111, v53, 0, vcc
	v_add_f32_e32 v71, 1.0, v71
	v_rcp_f32_e32 v71, v71
	v_cndmask_b32_e64 v86, v50, 0, vcc
	v_cndmask_b32_e64 v87, v51, 0, vcc
	v_cndmask_b32_e64 v88, v206, 0, s[62:63]
	v_mul_f32_e32 v71, v72, v71
	v_mul_f32_e32 v72, 0xbfb8aa3b, v73
	v_exp_f32_e32 v72, v72
	v_cndmask_b32_e64 v89, v207, 0, s[62:63]
	s_andn2_b64 vcc, exec, s[12:13]
	v_add_f32_e32 v72, 1.0, v72
	v_rcp_f32_e32 v72, v72
	s_waitcnt vmcnt(0)
	v_pk_fma_f32 v[78:79], v[60:61], v[96:97], v[78:79]
	v_mul_f32_e32 v72, v73, v72
	v_mul_f32_e32 v73, 0xbfb8aa3b, v66
	v_exp_f32_e32 v73, v73
	v_pk_fma_f32 v[78:79], v[92:93], v[110:111], v[78:79]
	v_pk_fma_f32 v[76:77], v[58:59], v[94:95], v[76:77]
	v_pk_fma_f32 v[78:79], v[82:83], v[112:113], v[78:79]
	v_add_f32_e32 v73, 1.0, v73
	v_rcp_f32_e32 v73, v73
	v_pk_fma_f32 v[76:77], v[90:91], v[86:87], v[76:77]
	v_mov_b32_e32 v110, 0
	v_pk_fma_f32 v[76:77], v[80:81], v[88:89], v[76:77]
	v_mul_f32_e32 v66, v66, v73
	v_mul_f32_e32 v73, 0xbfb8aa3b, v67
	v_exp_f32_e32 v73, v73
	v_mul_f32_e32 v66, v78, v66
	v_mul_f32_e32 v71, v76, v71
	v_mul_f32_e32 v72, v77, v72
	v_add_f32_e32 v73, 1.0, v73
	v_rcp_f32_e32 v73, v73
	v_mov_b32_e32 v76, 0
	v_mov_b32_e32 v77, 0
	v_mov_b32_e32 v78, 0
	v_mul_f32_e32 v67, v67, v73
	v_mul_f32_e32 v67, v79, v67
	v_cvt_pk_bf16_f32 v89, v66, v67
	v_cndmask_b32_e64 v66, 0, 1, s[12:13]
	v_cmp_ne_u32_e64 s[62:63], 1, v66
	v_mov_b32_e32 v79, 0
	v_mov_b32_e32 v111, 0
	v_mov_b32_e32 v112, 0
	v_mov_b32_e32 v113, 0
	v_cvt_pk_bf16_f32 v88, v71, v72
	s_cbranch_vccnz .LBB0_1200
	ds_read_b128 v[110:113], v219 offset:3072
	ds_read_b128 v[76:79], v219 offset:2048

.LBB0_1202:
	ds_read_b32 v86, v231
	s_waitcnt lgkmcnt(2)
	v_mov_b32_dpp v118, v46 row_shr:1 row_mask:0xf bank_mask:0xf
	v_mov_b32_dpp v119, v47 row_shr:1 row_mask:0xf bank_mask:0xf
	s_waitcnt lgkmcnt(1)
	v_mov_b32_dpp v70, v38 row_shr:1 row_mask:0xf bank_mask:0xf
	v_mov_b32_dpp v71, v39 row_shr:1 row_mask:0xf bank_mask:0xf
	s_waitcnt lgkmcnt(0)
	v_and_b32_e32 v66, 15, v86
	v_mul_u32_u24_e32 v66, 0x1600, v66
	v_lshlrev_b32_e32 v146, 2, v66
	v_lshl_add_u64 v[66:67], s[68:69], 0, v[146:147]
	v_lshl_add_u64 v[66:67], v[66:67], 0, v[114:115]
	global_load_dwordx4 v[122:125], v[66:67], off
	global_load_dwordx4 v[252:255], v[66:67], off offset:512
	v_and_b32_e32 v87, 16, v86
	v_cmp_eq_u32_e32 vcc, 0, v87
	v_and_b32_e32 v86, 32, v86
	v_cmp_eq_u32_e64 s[0:1], 0, v86
	v_cndmask_b32_e64 v86, v110, 0, vcc
	v_cndmask_b32_e64 v87, v111, 0, vcc
	v_cndmask_b32_e64 v126, v112, 0, vcc
	v_cndmask_b32_e64 v127, v113, 0, vcc
	v_cndmask_b32_e64 v76, v76, 0, s[0:1]
	v_cndmask_b32_e64 v77, v77, 0, s[0:1]
	v_cndmask_b32_e64 v78, v78, 0, s[0:1]
	v_cndmask_b32_e64 v79, v79, 0, s[0:1]
	v_cndmask_b32_e64 v70, v70, 0, s[0:1]
	v_cndmask_b32_e64 v71, v71, 0, s[0:1]
	v_mov_b32_dpp v120, v48 row_shr:1 row_mask:0xf bank_mask:0xf
	v_mov_b32_dpp v121, v49 row_shr:1 row_mask:0xf bank_mask:0xf
	v_mov_b32_dpp v72, v40 row_shr:1 row_mask:0xf bank_mask:0xf
	v_mov_b32_dpp v73, v41 row_shr:1 row_mask:0xf bank_mask:0xf
	v_cndmask_b32_e64 v72, v72, 0, s[0:1]
	v_cndmask_b32_e64 v73, v73, 0, s[0:1]
	v_mov_b32_e32 v116, 0
	v_mov_b32_e32 v128, 0
	v_mov_b32_e32 v129, 0
	v_mov_b32_e32 v130, 0
	v_mov_b32_e32 v131, 0
	s_waitcnt vmcnt(0)
	v_pk_fma_f32 v[124:125], v[196:197], v[108:109], v[124:125]
	v_pk_fma_f32 v[122:123], v[194:195], v[106:107], v[122:123]
	s_nop 0
	v_pk_fma_f32 v[86:87], v[102:103], v[86:87], v[122:123]
	v_pk_fma_f32 v[122:123], v[104:105], v[126:127], v[124:125]
	v_pk_fma_f32 v[86:87], v[98:99], v[76:77], v[86:87]
	v_pk_fma_f32 v[122:123], v[100:101], v[78:79], v[122:123]
	v_mov_b64_e32 v[76:77], v[252:253]
	v_mov_b64_e32 v[78:79], v[254:255]
	v_cndmask_b32_e64 v66, v118, 0, vcc
	v_cndmask_b32_e64 v67, v119, 0, vcc
	v_cndmask_b32_e64 v124, v120, 0, vcc
	v_cndmask_b32_e64 v125, v121, 0, vcc
	v_mov_b32_e32 v126, 0
	v_mov_b32_e32 v127, 0
	s_waitcnt vmcnt(0)
	v_pk_fma_f32 v[76:77], v[198:199], v[94:95], v[76:77]
	s_nop 0
	v_pk_fma_f32 v[66:67], v[90:91], v[66:67], v[76:77]
	v_pk_fma_f32 v[78:79], v[200:201], v[96:97], v[78:79]
	v_pk_fma_f32 v[66:67], v[80:81], v[70:71], v[66:67]
	v_mul_f32_e32 v70, 0xbfb8aa3b, v86
	v_exp_f32_e32 v70, v70
	v_mul_f32_e32 v71, 0xbfb8aa3b, v123
	v_exp_f32_e32 v71, v71
	v_pk_fma_f32 v[78:79], v[92:93], v[124:125], v[78:79]
	v_add_f32_e32 v70, 1.0, v70
	v_rcp_f32_e32 v70, v70
	v_add_f32_e32 v71, 1.0, v71
	v_rcp_f32_e32 v71, v71
	v_pk_fma_f32 v[72:73], v[82:83], v[72:73], v[78:79]
	v_mul_f32_e32 v70, v86, v70
	v_mul_f32_e32 v66, v66, v70
	v_mul_f32_e32 v70, 0xbfb8aa3b, v87
	v_exp_f32_e32 v70, v70
	v_mul_f32_e32 v71, v123, v71
	v_mul_f32_e32 v71, v73, v71
	v_mov_b32_e32 v124, 0
	v_add_f32_e32 v70, 1.0, v70
	v_rcp_f32_e32 v70, v70
	v_mov_b32_e32 v125, 0
	v_mul_f32_e32 v70, v87, v70
	v_mul_f32_e32 v67, v67, v70
	v_mul_f32_e32 v70, 0xbfb8aa3b, v122
	v_exp_f32_e32 v70, v70
	v_cvt_pk_bf16_f32 v78, v66, v67
	s_nop 0
	v_add_f32_e32 v70, 1.0, v70
	v_rcp_f32_e32 v70, v70
	s_nop 0
	v_mul_f32_e32 v70, v122, v70
	v_mul_f32_e32 v70, v72, v70
	v_cvt_pk_bf16_f32 v79, v70, v71
	ds_read_b32 v70, v233
	s_waitcnt lgkmcnt(0)
	v_and_b32_e32 v66, 15, v70
	v_mul_u32_u24_e32 v66, 0x1600, v66
	v_lshlrev_b32_e32 v146, 2, v66
	v_lshl_add_u64 v[66:67], s[68:69], 0, v[146:147]
	v_lshl_add_u64 v[66:67], v[66:67], 0, v[114:115]
	v_and_b32_e32 v71, 16, v70
	v_and_b32_e32 v70, 32, v70
	v_cmp_eq_u32_e32 vcc, 0, v71
	v_cmp_eq_u32_e64 s[0:1], 0, v70
	global_load_dwordx4 v[70:73], v[66:67], off
	global_load_dwordx4 v[252:255], v[66:67], off offset:512
	v_cndmask_b32_e64 v76, v194, 0, vcc
	v_cndmask_b32_e64 v86, v110, 0, s[0:1]
	v_cndmask_b32_e64 v77, v195, 0, vcc
	v_cndmask_b32_e64 v87, v111, 0, s[0:1]
	v_cndmask_b32_e64 v110, v196, 0, vcc
	v_cndmask_b32_e64 v111, v197, 0, vcc
	v_cndmask_b32_e64 v112, v112, 0, s[0:1]
	v_cndmask_b32_e64 v113, v113, 0, s[0:1]
	s_waitcnt vmcnt(0)
	v_pk_fma_f32 v[72:73], v[188:189], v[108:109], v[72:73]
	v_pk_fma_f32 v[70:71], v[186:187], v[106:107], v[70:71]
	v_pk_fma_f32 v[72:73], v[104:105], v[110:111], v[72:73]
	v_pk_fma_f32 v[70:71], v[102:103], v[76:77], v[70:71]
	v_pk_fma_f32 v[76:77], v[100:101], v[112:113], v[72:73]
	v_pk_fma_f32 v[86:87], v[98:99], v[86:87], v[70:71]
	v_mov_b64_e32 v[70:71], v[252:253]
	v_mov_b64_e32 v[72:73], v[254:255]
	v_cndmask_b32_e64 v66, v198, 0, vcc
	v_cndmask_b32_e64 v67, v199, 0, vcc
	v_cndmask_b32_e64 v112, v200, 0, vcc
	v_cndmask_b32_e64 v113, v201, 0, vcc
	v_cndmask_b32_e64 v110, v118, 0, s[0:1]
	v_cndmask_b32_e64 v111, v119, 0, s[0:1]
	v_cndmask_b32_e64 v118, v120, 0, s[0:1]
	v_cndmask_b32_e64 v119, v121, 0, s[0:1]
	s_waitcnt vmcnt(0)
	v_pk_fma_f32 v[72:73], v[192:193], v[96:97], v[72:73]
	v_pk_fma_f32 v[70:71], v[190:191], v[94:95], v[70:71]
	s_nop 0
	v_pk_fma_f32 v[66:67], v[90:91], v[66:67], v[70:71]
	v_pk_fma_f32 v[70:71], v[92:93], v[112:113], v[72:73]
	v_mul_f32_e32 v72, 0xbfb8aa3b, v86
	v_exp_f32_e32 v72, v72
	v_pk_fma_f32 v[66:67], v[80:81], v[110:111], v[66:67]
	v_pk_fma_f32 v[70:71], v[82:83], v[118:119], v[70:71]
	v_add_f32_e32 v72, 1.0, v72
	v_rcp_f32_e32 v72, v72
	s_nop 0
	v_mul_f32_e32 v72, v86, v72
	v_mul_f32_e32 v66, v66, v72
	v_mul_f32_e32 v72, 0xbfb8aa3b, v87
	v_exp_f32_e32 v72, v72
	s_nop 0
	v_add_f32_e32 v72, 1.0, v72
	v_rcp_f32_e32 v72, v72
	s_nop 0
	v_mul_f32_e32 v72, v87, v72
	v_mul_f32_e32 v67, v67, v72
	v_mul_f32_e32 v72, 0xbfb8aa3b, v76
	v_exp_f32_e32 v72, v72
	s_nop 0
	v_add_f32_e32 v72, 1.0, v72
	v_rcp_f32_e32 v72, v72
	s_nop 0
	v_mul_f32_e32 v72, v76, v72
	v_mul_f32_e32 v70, v70, v72
	v_mul_f32_e32 v72, 0xbfb8aa3b, v77
	v_exp_f32_e32 v72, v72
	s_nop 0
	v_add_f32_e32 v72, 1.0, v72
	v_rcp_f32_e32 v72, v72
	s_nop 0
	v_mul_f32_e32 v72, v77, v72
	v_mul_f32_e32 v71, v71, v72
	v_cvt_pk_bf16_f32 v73, v70, v71
	ds_read_b32 v70, v235
	v_cvt_pk_bf16_f32 v72, v66, v67
	s_waitcnt lgkmcnt(0)
	v_and_b32_e32 v66, 15, v70
	v_mul_u32_u24_e32 v66, 0x1600, v66
	v_lshlrev_b32_e32 v146, 2, v66
	v_lshl_add_u64 v[66:67], s[68:69], 0, v[146:147]
	v_lshl_add_u64 v[66:67], v[66:67], 0, v[114:115]
	global_load_dwordx4 v[110:113], v[66:67], off
	global_load_dwordx4 v[252:255], v[66:67], off offset:512
	v_and_b32_e32 v71, 16, v70
	v_cmp_eq_u32_e32 vcc, 0, v71
	v_and_b32_e32 v70, 32, v70
	v_cmp_eq_u32_e64 s[0:1], 0, v70
	v_cndmask_b32_e64 v70, v186, 0, vcc
	v_cndmask_b32_e64 v71, v187, 0, vcc
	v_cndmask_b32_e64 v86, v188, 0, vcc
	v_cndmask_b32_e64 v87, v189, 0, vcc
	v_cndmask_b32_e64 v76, v194, 0, s[0:1]
	v_cndmask_b32_e64 v77, v195, 0, s[0:1]
	v_cndmask_b32_e64 v118, v196, 0, s[0:1]
	v_cndmask_b32_e64 v119, v197, 0, s[0:1]
	v_cndmask_b32_e64 v120, v200, 0, s[0:1]
	v_cndmask_b32_e64 v121, v201, 0, s[0:1]
	s_waitcnt vmcnt(0)
	v_pk_fma_f32 v[112:113], v[36:37], v[108:109], v[112:113]
	v_pk_fma_f32 v[110:111], v[34:35], v[106:107], v[110:111]
	v_pk_fma_f32 v[86:87], v[104:105], v[86:87], v[112:113]
	v_pk_fma_f32 v[70:71], v[102:103], v[70:71], v[110:111]
	v_mov_b64_e32 v[110:111], v[252:253]
	v_mov_b64_e32 v[112:113], v[254:255]
	v_cndmask_b32_e64 v66, v190, 0, vcc
	v_cndmask_b32_e64 v67, v191, 0, vcc
	v_pk_fma_f32 v[70:71], v[98:99], v[76:77], v[70:71]
	v_cndmask_b32_e64 v76, v198, 0, s[0:1]
	v_cndmask_b32_e64 v77, v199, 0, s[0:1]
	v_pk_fma_f32 v[86:87], v[100:101], v[118:119], v[86:87]
	v_cndmask_b32_e64 v118, v192, 0, vcc
	v_cndmask_b32_e64 v119, v193, 0, vcc
	s_waitcnt vmcnt(0)
	v_pk_fma_f32 v[110:111], v[38:39], v[94:95], v[110:111]
	s_nop 0
	v_pk_fma_f32 v[66:67], v[90:91], v[66:67], v[110:111]
	v_pk_fma_f32 v[112:113], v[40:41], v[96:97], v[112:113]
	v_pk_fma_f32 v[66:67], v[80:81], v[76:77], v[66:67]
	v_mul_f32_e32 v76, 0xbfb8aa3b, v70
	v_exp_f32_e32 v76, v76
	v_pk_fma_f32 v[110:111], v[92:93], v[118:119], v[112:113]
	v_add_f32_e32 v76, 1.0, v76
	v_rcp_f32_e32 v76, v76
	v_pk_fma_f32 v[110:111], v[82:83], v[120:121], v[110:111]
	v_mul_f32_e32 v70, v70, v76
	v_mul_f32_e32 v66, v66, v70
	v_mul_f32_e32 v70, 0xbfb8aa3b, v71
	v_exp_f32_e32 v70, v70
	ds_read_b32 v76, v237
	v_add_f32_e32 v70, 1.0, v70
	v_rcp_f32_e32 v70, v70
	s_waitcnt lgkmcnt(0)
	v_and_b32_e32 v77, 16, v76
	v_cmp_eq_u32_e32 vcc, 0, v77
	v_mul_f32_e32 v70, v71, v70
	v_mul_f32_e32 v67, v67, v70
	v_mul_f32_e32 v70, 0xbfb8aa3b, v86
	v_exp_f32_e32 v70, v70
	v_mul_f32_e32 v71, 0xbfb8aa3b, v87
	v_exp_f32_e32 v71, v71
	v_cvt_pk_bf16_f32 v66, v66, v67
	v_add_f32_e32 v70, 1.0, v70
	v_rcp_f32_e32 v70, v70
	v_add_f32_e32 v71, 1.0, v71
	v_rcp_f32_e32 v71, v71
	v_cndmask_b32_e64 v77, v35, 0, vcc
	v_mul_f32_e32 v70, v86, v70
	v_mul_f32_e32 v70, v110, v70
	v_mul_f32_e32 v71, v87, v71
	v_mul_f32_e32 v71, v111, v71
	v_cvt_pk_bf16_f32 v67, v70, v71
	v_and_b32_e32 v70, 15, v76
	v_mul_u32_u24_e32 v70, 0x1600, v70
	v_lshlrev_b32_e32 v146, 2, v70
	v_lshl_add_u64 v[70:71], s[68:69], 0, v[146:147]
	v_lshl_add_u64 v[70:71], v[70:71], 0, v[114:115]
	global_load_dwordx4 v[110:113], v[70:71], off
	global_load_dwordx4 v[252:255], v[70:71], off offset:512
	v_and_b32_e32 v76, 32, v76
	v_cmp_eq_u32_e64 s[64:65], 0, v76
	v_cndmask_b32_e64 v76, v34, 0, vcc
	v_cndmask_b32_e64 v114, v36, 0, vcc
	v_cndmask_b32_e64 v115, v37, 0, vcc
	v_cndmask_b32_e64 v86, v186, 0, s[64:65]
	v_cndmask_b32_e64 v87, v187, 0, s[64:65]
	v_cndmask_b32_e64 v118, v188, 0, s[64:65]
	v_cndmask_b32_e64 v119, v189, 0, s[64:65]
	s_waitcnt vmcnt(0)
	v_pk_fma_f32 v[108:109], v[44:45], v[108:109], v[112:113]
	v_pk_fma_f32 v[106:107], v[42:43], v[106:107], v[110:111]
	s_nop 0
	v_pk_fma_f32 v[76:77], v[102:103], v[76:77], v[106:107]
	v_pk_fma_f32 v[102:103], v[104:105], v[114:115], v[108:109]
	v_pk_fma_f32 v[76:77], v[98:99], v[86:87], v[76:77]
	v_pk_fma_f32 v[102:103], v[100:101], v[118:119], v[102:103]
	v_mov_b64_e32 v[98:99], v[252:253]
	v_mov_b64_e32 v[100:101], v[254:255]
	v_cndmask_b32_e64 v70, v38, 0, vcc
	v_cndmask_b32_e64 v71, v39, 0, vcc
	v_cndmask_b32_e64 v86, v190, 0, s[64:65]
	v_cndmask_b32_e64 v87, v191, 0, s[64:65]
	v_cndmask_b32_e64 v104, v40, 0, vcc
	v_cndmask_b32_e64 v105, v41, 0, vcc
	v_cndmask_b32_e64 v106, v192, 0, s[64:65]
	v_cndmask_b32_e64 v107, v193, 0, s[64:65]
	s_and_b64 vcc, exec, s[60:61]
	s_waitcnt vmcnt(0)
	v_pk_fma_f32 v[94:95], v[46:47], v[94:95], v[98:99]
	s_nop 0
	v_pk_fma_f32 v[70:71], v[90:91], v[70:71], v[94:95]
	v_pk_fma_f32 v[96:97], v[48:49], v[96:97], v[100:101]
	v_pk_fma_f32 v[70:71], v[80:81], v[86:87], v[70:71]
	v_mul_f32_e32 v80, 0xbfb8aa3b, v76
	v_exp_f32_e32 v80, v80
	v_pk_fma_f32 v[90:91], v[92:93], v[104:105], v[96:97]
	v_add_f32_e32 v80, 1.0, v80
	v_rcp_f32_e32 v80, v80
	v_pk_fma_f32 v[82:83], v[82:83], v[106:107], v[90:91]
	v_mul_f32_e32 v76, v76, v80
	v_mul_f32_e32 v70, v70, v76
	v_mul_f32_e32 v76, 0xbfb8aa3b, v77
	v_exp_f32_e32 v76, v76
	s_nop 0
	v_add_f32_e32 v76, 1.0, v76
	v_rcp_f32_e32 v76, v76
	s_nop 0
	v_mul_f32_e32 v76, v77, v76
	v_mul_f32_e32 v71, v71, v76
	v_mul_f32_e32 v76, 0xbfb8aa3b, v102
	v_exp_f32_e32 v76, v76
	v_mul_f32_e32 v77, 0xbfb8aa3b, v103
	v_exp_f32_e32 v77, v77
	v_add_f32_e32 v76, 1.0, v76
	v_rcp_f32_e32 v76, v76
	v_add_f32_e32 v77, 1.0, v77
	v_rcp_f32_e32 v77, v77
	v_mul_f32_e32 v76, v102, v76
	v_mul_f32_e32 v76, v82, v76
	v_cvt_pk_bf16_f32 v82, v70, v71
	v_or_b32_e32 v70, 4, v184
	v_mul_f32_e32 v77, v103, v77
	v_ashrrev_i32_e32 v71, 31, v70
	v_mul_f32_e32 v77, v83, v77
	v_lshlrev_b64 v[70:71], 2, v[70:71]
	v_cvt_pk_bf16_f32 v83, v76, v77
	v_lshl_add_u64 v[76:77], s[4:5], 0, v[70:71]
	global_load_dwordx4 v[104:107], v[76:77], off
	v_lshl_add_u64 v[76:77], s[96:97], 0, v[70:71]
	v_lshl_add_u64 v[70:71], s[78:79], 0, v[70:71]
	global_load_dwordx4 v[108:111], v[76:77], off
	global_load_dwordx4 v[112:115], v[70:71], off
	v_or_b32_e32 v70, 0x84, v184
	v_ashrrev_i32_e32 v71, 31, v70
	v_lshlrev_b64 v[70:71], 2, v[70:71]
	v_lshl_add_u64 v[76:77], s[4:5], 0, v[70:71]
	global_load_dwordx4 v[92:95], v[76:77], off
	v_lshl_add_u64 v[76:77], s[96:97], 0, v[70:71]
	v_lshl_add_u64 v[70:71], s[78:79], 0, v[70:71]
	global_load_dwordx4 v[96:99], v[76:77], off
	global_load_dwordx4 v[100:103], v[70:71], off
	s_cbranch_vccnz .LBB0_1204
	ds_read_b128 v[124:127], v221 offset:16
	ds_read_b128 v[128:131], v222 offset:16

.LBB0_1206:
	ds_read_b32 v243, v223
	s_waitcnt lgkmcnt(2)
	v_mov_b32_dpp v120, v26 row_shr:1 row_mask:0xf bank_mask:0xf
	v_mov_b32_dpp v121, v27 row_shr:1 row_mask:0xf bank_mask:0xf
	s_waitcnt lgkmcnt(1)
	v_mov_b32_dpp v116, v18 row_shr:1 row_mask:0xf bank_mask:0xf
	v_mov_b32_dpp v117, v19 row_shr:1 row_mask:0xf bank_mask:0xf
	s_waitcnt lgkmcnt(0)
	v_and_b32_e32 v70, 15, v243
	v_mul_u32_u24_e32 v70, 0x1600, v70
	v_lshlrev_b32_e32 v146, 2, v70
	v_lshl_add_u64 v[70:71], s[68:69], 0, v[146:147]
	v_lshl_add_u64 v[70:71], v[184:185], 2, v[70:71]
	global_load_dwordx4 v[244:247], v[70:71], off offset:16
	global_load_dwordx4 v[252:255], v[70:71], off offset:528
	v_and_b32_e32 v76, 16, v243
	v_cmp_eq_u32_e32 vcc, 0, v76
	v_and_b32_e32 v76, 32, v243
	v_cmp_eq_u32_e64 s[0:1], 0, v76
	v_cndmask_b32_e64 v76, v124, 0, vcc
	v_cndmask_b32_e64 v77, v125, 0, vcc
	v_cndmask_b32_e64 v80, v128, 0, s[0:1]
	v_cndmask_b32_e64 v81, v129, 0, s[0:1]
	v_cndmask_b32_e64 v86, v126, 0, vcc
	v_cndmask_b32_e64 v90, v130, 0, s[0:1]
	v_cndmask_b32_e64 v87, v127, 0, vcc
	v_cndmask_b32_e64 v91, v131, 0, s[0:1]
	v_mov_b32_dpp v122, v28 row_shr:1 row_mask:0xf bank_mask:0xf
	v_mov_b32_dpp v118, v20 row_shr:1 row_mask:0xf bank_mask:0xf
	v_mov_b32_dpp v123, v29 row_shr:1 row_mask:0xf bank_mask:0xf
	v_mov_b32_dpp v119, v21 row_shr:1 row_mask:0xf bank_mask:0xf
	s_waitcnt vmcnt(0)
	v_pk_fma_f32 v[128:129], v[182:183], v[114:115], v[246:247]
	v_pk_fma_f32 v[130:131], v[178:179], v[112:113], v[244:245]
	v_pk_fma_f32 v[86:87], v[110:111], v[86:87], v[128:129]
	v_pk_fma_f32 v[76:77], v[108:109], v[76:77], v[130:131]
	v_mov_b64_e32 v[128:129], v[252:253]
	v_mov_b64_e32 v[130:131], v[254:255]
	v_cndmask_b32_e64 v70, v120, 0, vcc
	v_cndmask_b32_e64 v71, v121, 0, vcc
	v_pk_fma_f32 v[76:77], v[104:105], v[80:81], v[76:77]
	v_cndmask_b32_e64 v80, v116, 0, s[0:1]
	v_cndmask_b32_e64 v81, v117, 0, s[0:1]
	v_pk_fma_f32 v[86:87], v[106:107], v[90:91], v[86:87]
	v_cndmask_b32_e64 v90, v122, 0, vcc
	v_cndmask_b32_e64 v116, v118, 0, s[0:1]
	v_cndmask_b32_e64 v91, v123, 0, vcc
	v_cndmask_b32_e64 v117, v119, 0, s[0:1]
	s_waitcnt vmcnt(0)
	v_pk_fma_f32 v[128:129], v[176:177], v[100:101], v[128:129]
	s_nop 0
	v_pk_fma_f32 v[70:71], v[96:97], v[70:71], v[128:129]
	v_pk_fma_f32 v[118:119], v[180:181], v[102:103], v[130:131]
	v_pk_fma_f32 v[70:71], v[92:93], v[80:81], v[70:71]
	v_mul_f32_e32 v80, 0xbfb8aa3b, v76
	v_exp_f32_e32 v80, v80
	v_pk_fma_f32 v[90:91], v[98:99], v[90:91], v[118:119]
	v_add_f32_e32 v80, 1.0, v80
	v_rcp_f32_e32 v80, v80
	v_pk_fma_f32 v[90:91], v[94:95], v[116:117], v[90:91]
	v_mul_f32_e32 v76, v76, v80
	v_mul_f32_e32 v70, v70, v76
	v_mul_f32_e32 v76, 0xbfb8aa3b, v77
	v_exp_f32_e32 v76, v76
	s_nop 0
	v_add_f32_e32 v76, 1.0, v76
	v_rcp_f32_e32 v76, v76
	s_nop 0
	v_mul_f32_e32 v76, v77, v76
	v_mul_f32_e32 v71, v71, v76
	v_mul_f32_e32 v76, 0xbfb8aa3b, v86
	v_exp_f32_e32 v76, v76
	v_mul_f32_e32 v77, 0xbfb8aa3b, v87
	v_exp_f32_e32 v77, v77
	v_add_f32_e32 v76, 1.0, v76
	v_rcp_f32_e32 v76, v76
	v_add_f32_e32 v77, 1.0, v77
	v_rcp_f32_e32 v77, v77
	v_mul_f32_e32 v76, v86, v76
	v_cvt_pk_bf16_f32 v86, v70, v71
	v_and_b32_e32 v70, 64, v243
	v_mul_f32_e32 v77, v87, v77
	v_cmp_ne_u32_e32 vcc, 0, v70
	v_mul_f32_e32 v76, v90, v76
	v_mul_f32_e32 v77, v91, v77
	v_cvt_pk_bf16_f32 v87, v76, v77
	s_and_saveexec_b64 s[0:1], vcc
	s_cbranch_execz .LBB0_1208
	v_add_u32_e32 v76, s17, v220
	v_mov_b64_e32 v[70:71], s[70:71]
	v_mad_i64_i32 v[70:71], s[38:39], v76, s34, v[70:71]
	s_lshl_b32 s38, s72, 7
	s_ashr_i32 s39, s38, 31
	v_lshl_add_u64 v[70:71], s[38:39], 1, v[70:71]
	v_lshlrev_b32_e32 v146, 1, v148
	v_lshl_add_u64 v[70:71], v[70:71], 0, v[146:147]
	global_store_dwordx4 v[70:71], v[84:87], off
.LBB0_1208:
	s_or_b64 exec, exec, s[0:1]
	ds_read_b32 v128, v225
	s_waitcnt lgkmcnt(0)
	v_and_b32_e32 v70, 15, v128
	v_mul_u32_u24_e32 v70, 0x1600, v70
	v_lshlrev_b32_e32 v146, 2, v70
	v_lshl_add_u64 v[70:71], s[68:69], 0, v[146:147]
	v_lshl_add_u64 v[70:71], v[184:185], 2, v[70:71]
	global_load_dwordx4 v[84:87], v[70:71], off offset:16
	global_load_dwordx4 v[252:255], v[70:71], off offset:528
	v_and_b32_e32 v76, 16, v128
	v_cmp_eq_u32_e32 vcc, 0, v76
	v_and_b32_e32 v76, 32, v128
	v_cmp_eq_u32_e64 s[0:1], 0, v76
	v_cndmask_b32_e64 v90, v182, 0, vcc
	v_cndmask_b32_e64 v91, v183, 0, vcc
	v_cndmask_b32_e64 v76, v178, 0, vcc
	v_cndmask_b32_e64 v77, v179, 0, vcc
	v_cndmask_b32_e64 v116, v126, 0, s[0:1]
	v_cndmask_b32_e64 v117, v127, 0, s[0:1]
	v_cndmask_b32_e64 v80, v124, 0, s[0:1]
	v_cndmask_b32_e64 v81, v125, 0, s[0:1]
	v_cndmask_b32_e64 v118, v122, 0, s[0:1]
	v_cndmask_b32_e64 v119, v123, 0, s[0:1]
	s_waitcnt vmcnt(0)
	v_pk_fma_f32 v[86:87], v[174:175], v[114:115], v[86:87]
	v_pk_fma_f32 v[84:85], v[172:173], v[112:113], v[84:85]
	v_pk_fma_f32 v[86:87], v[110:111], v[90:91], v[86:87]
	v_pk_fma_f32 v[76:77], v[108:109], v[76:77], v[84:85]
	v_pk_fma_f32 v[90:91], v[106:107], v[116:117], v[86:87]
	v_mov_b64_e32 v[84:85], v[252:253]
	v_mov_b64_e32 v[86:87], v[254:255]
	v_cndmask_b32_e64 v70, v176, 0, vcc
	v_cndmask_b32_e64 v71, v177, 0, vcc
	v_pk_fma_f32 v[76:77], v[104:105], v[80:81], v[76:77]
	v_cndmask_b32_e64 v80, v120, 0, s[0:1]
	v_cndmask_b32_e64 v81, v121, 0, s[0:1]
	v_cndmask_b32_e64 v116, v180, 0, vcc
	v_cndmask_b32_e64 v117, v181, 0, vcc
	s_waitcnt vmcnt(0)
	v_pk_fma_f32 v[84:85], v[168:169], v[100:101], v[84:85]
	s_nop 0
	v_pk_fma_f32 v[70:71], v[96:97], v[70:71], v[84:85]
	v_pk_fma_f32 v[86:87], v[170:171], v[102:103], v[86:87]
	v_pk_fma_f32 v[70:71], v[92:93], v[80:81], v[70:71]
	v_mul_f32_e32 v80, 0xbfb8aa3b, v76
	v_exp_f32_e32 v80, v80
	v_pk_fma_f32 v[86:87], v[98:99], v[116:117], v[86:87]
	v_add_f32_e32 v80, 1.0, v80
	v_rcp_f32_e32 v80, v80
	v_pk_fma_f32 v[84:85], v[94:95], v[118:119], v[86:87]
	v_mul_f32_e32 v76, v76, v80
	v_mul_f32_e32 v70, v70, v76
	v_mul_f32_e32 v76, 0xbfb8aa3b, v77
	v_exp_f32_e32 v76, v76
	s_nop 0
	v_add_f32_e32 v76, 1.0, v76
	v_rcp_f32_e32 v76, v76
	s_nop 0
	v_mul_f32_e32 v76, v77, v76
	v_mul_f32_e32 v71, v71, v76
	v_mul_f32_e32 v76, 0xbfb8aa3b, v90
	v_exp_f32_e32 v76, v76
	s_nop 0
	v_add_f32_e32 v76, 1.0, v76
	v_rcp_f32_e32 v76, v76
	s_nop 0
	v_mul_f32_e32 v76, v90, v76
	v_mul_f32_e32 v77, v84, v76
	v_mul_f32_e32 v76, 0xbfb8aa3b, v91
	v_exp_f32_e32 v76, v76
	s_nop 0
	v_add_f32_e32 v76, 1.0, v76
	v_rcp_f32_e32 v76, v76
	s_nop 0
	v_mul_f32_e32 v76, v91, v76
	v_mul_f32_e32 v80, v85, v76
	v_cvt_pk_bf16_f32 v76, v70, v71
	v_and_b32_e32 v70, 64, v128
	v_cmp_ne_u32_e32 vcc, 0, v70
	v_cvt_pk_bf16_f32 v77, v77, v80
	s_and_saveexec_b64 s[0:1], vcc
	s_cbranch_execz .LBB0_1210
	v_add_u32_e32 v80, s17, v224
	v_mov_b64_e32 v[70:71], s[70:71]
	v_mad_i64_i32 v[70:71], s[38:39], v80, s34, v[70:71]
	s_lshl_b32 s38, s72, 7
	s_ashr_i32 s39, s38, 31
	v_lshl_add_u64 v[70:71], s[38:39], 1, v[70:71]
	v_lshlrev_b32_e32 v146, 1, v148
	v_lshl_add_u64 v[70:71], v[70:71], 0, v[146:147]
	global_store_dwordx4 v[70:71], v[74:77], off
.LBB0_1210:
	s_or_b64 exec, exec, s[0:1]
	ds_read_b32 v118, v227
	s_waitcnt lgkmcnt(0)
	v_and_b32_e32 v70, 15, v118
	v_mul_u32_u24_e32 v70, 0x1600, v70
	v_lshlrev_b32_e32 v146, 2, v70
	v_lshl_add_u64 v[70:71], s[68:69], 0, v[146:147]
	v_and_b32_e32 v74, 16, v118
	v_lshl_add_u64 v[70:71], v[184:185], 2, v[70:71]
	v_cmp_eq_u32_e32 vcc, 0, v74
	v_and_b32_e32 v74, 32, v118
	v_cmp_eq_u32_e64 s[0:1], 0, v74
	global_load_dwordx4 v[74:77], v[70:71], off offset:16
	global_load_dwordx4 v[252:255], v[70:71], off offset:528
	v_cndmask_b32_e64 v80, v172, 0, vcc
	v_cndmask_b32_e64 v81, v173, 0, vcc
	v_cndmask_b32_e64 v86, v174, 0, vcc
	v_cndmask_b32_e64 v87, v175, 0, vcc
	v_cndmask_b32_e64 v84, v178, 0, s[0:1]
	v_cndmask_b32_e64 v85, v179, 0, s[0:1]
	v_cndmask_b32_e64 v90, v182, 0, s[0:1]
	v_cndmask_b32_e64 v91, v183, 0, s[0:1]
	v_cndmask_b32_e64 v116, v180, 0, s[0:1]
	v_cndmask_b32_e64 v117, v181, 0, s[0:1]
	s_waitcnt vmcnt(0)
	v_pk_fma_f32 v[76:77], v[24:25], v[114:115], v[76:77]
	v_pk_fma_f32 v[74:75], v[22:23], v[112:113], v[74:75]
	v_pk_fma_f32 v[76:77], v[110:111], v[86:87], v[76:77]
	v_pk_fma_f32 v[74:75], v[108:109], v[80:81], v[74:75]
	v_pk_fma_f32 v[80:81], v[106:107], v[90:91], v[76:77]
	v_pk_fma_f32 v[84:85], v[104:105], v[84:85], v[74:75]
	v_mov_b64_e32 v[74:75], v[252:253]
	v_mov_b64_e32 v[76:77], v[254:255]
	v_cndmask_b32_e64 v90, v170, 0, vcc
	v_cndmask_b32_e64 v91, v171, 0, vcc
	v_cndmask_b32_e64 v70, v168, 0, vcc
	v_cndmask_b32_e64 v71, v169, 0, vcc
	v_cndmask_b32_e64 v86, v176, 0, s[0:1]
	v_cndmask_b32_e64 v87, v177, 0, s[0:1]
	s_waitcnt vmcnt(0)
	v_pk_fma_f32 v[76:77], v[20:21], v[102:103], v[76:77]
	v_pk_fma_f32 v[74:75], v[18:19], v[100:101], v[74:75]
	v_pk_fma_f32 v[76:77], v[98:99], v[90:91], v[76:77]
	v_pk_fma_f32 v[70:71], v[96:97], v[70:71], v[74:75]
	v_pk_fma_f32 v[74:75], v[94:95], v[116:117], v[76:77]
	v_mul_f32_e32 v76, 0xbfb8aa3b, v84
	v_exp_f32_e32 v76, v76
	v_pk_fma_f32 v[70:71], v[92:93], v[86:87], v[70:71]
	v_add_f32_e32 v76, 1.0, v76
	v_rcp_f32_e32 v76, v76
	s_nop 0
	v_mul_f32_e32 v76, v84, v76
	v_mul_f32_e32 v70, v70, v76
	v_mul_f32_e32 v76, 0xbfb8aa3b, v85
	v_exp_f32_e32 v76, v76
	s_nop 0
	v_add_f32_e32 v76, 1.0, v76
	v_rcp_f32_e32 v76, v76
	s_nop 0
	v_mul_f32_e32 v76, v85, v76
	v_mul_f32_e32 v71, v71, v76
	v_mul_f32_e32 v76, 0xbfb8aa3b, v80
	v_exp_f32_e32 v76, v76
	v_cvt_pk_bf16_f32 v70, v70, v71
	s_nop 0
	v_add_f32_e32 v76, 1.0, v76
	v_rcp_f32_e32 v76, v76
	s_nop 0
	v_mul_f32_e32 v76, v80, v76
	v_mul_f32_e32 v74, v74, v76
	v_mul_f32_e32 v76, 0xbfb8aa3b, v81
	v_exp_f32_e32 v76, v76
	s_nop 0
	v_add_f32_e32 v76, 1.0, v76
	v_rcp_f32_e32 v76, v76
	s_nop 0
	v_mul_f32_e32 v76, v81, v76
	v_mul_f32_e32 v75, v75, v76
	v_cvt_pk_bf16_f32 v71, v74, v75
	v_and_b32_e32 v74, 64, v118
	v_cmp_ne_u32_e32 vcc, 0, v74
	s_and_saveexec_b64 s[0:1], vcc
	s_cbranch_execz .LBB0_1212
	v_add_u32_e32 v76, s17, v226
	v_mov_b64_e32 v[74:75], s[70:71]
	v_mad_i64_i32 v[74:75], s[38:39], v76, s34, v[74:75]
	s_lshl_b32 s38, s72, 7
	s_ashr_i32 s39, s38, 31
	v_lshl_add_u64 v[74:75], s[38:39], 1, v[74:75]
	v_lshlrev_b32_e32 v146, 1, v148
	v_lshl_add_u64 v[74:75], v[74:75], 0, v[146:147]
	global_store_dwordx4 v[74:75], v[68:71], off
.LBB0_1212:
	s_or_b64 exec, exec, s[0:1]
	ds_read_b32 v116, v229
	s_waitcnt lgkmcnt(0)
	v_and_b32_e32 v68, 15, v116
	v_mul_u32_u24_e32 v68, 0x1600, v68
	v_lshlrev_b32_e32 v146, 2, v68
	v_lshl_add_u64 v[68:69], s[68:69], 0, v[146:147]
	v_lshl_add_u64 v[74:75], v[184:185], 2, v[68:69]
	v_and_b32_e32 v68, 16, v116
	v_cmp_eq_u32_e32 vcc, 0, v68
	v_and_b32_e32 v68, 32, v116
	v_cmp_eq_u32_e64 s[0:1], 0, v68
	global_load_dwordx4 v[68:71], v[74:75], off offset:16
	global_load_dwordx4 v[252:255], v[74:75], off offset:528
	v_cndmask_b32_e64 v76, v22, 0, vcc
	v_cndmask_b32_e64 v77, v23, 0, vcc
	v_cndmask_b32_e64 v84, v24, 0, vcc
	v_cndmask_b32_e64 v85, v25, 0, vcc
	v_cndmask_b32_e64 v80, v172, 0, s[0:1]
	v_cndmask_b32_e64 v81, v173, 0, s[0:1]
	v_cndmask_b32_e64 v86, v174, 0, s[0:1]
	v_cndmask_b32_e64 v87, v175, 0, s[0:1]
	v_cndmask_b32_e64 v90, v170, 0, s[0:1]
	v_cndmask_b32_e64 v91, v171, 0, s[0:1]
	s_waitcnt vmcnt(0)
	v_pk_fma_f32 v[70:71], v[32:33], v[114:115], v[70:71]
	v_pk_fma_f32 v[68:69], v[30:31], v[112:113], v[68:69]
	v_pk_fma_f32 v[70:71], v[110:111], v[84:85], v[70:71]
	v_pk_fma_f32 v[68:69], v[108:109], v[76:77], v[68:69]
	v_pk_fma_f32 v[76:77], v[106:107], v[86:87], v[70:71]
	v_pk_fma_f32 v[80:81], v[104:105], v[80:81], v[68:69]
	v_mov_b64_e32 v[68:69], v[252:253]
	v_mov_b64_e32 v[70:71], v[254:255]
	v_cndmask_b32_e64 v74, v18, 0, vcc
	v_cndmask_b32_e64 v75, v19, 0, vcc
	v_cndmask_b32_e64 v84, v168, 0, s[0:1]
	v_cndmask_b32_e64 v85, v169, 0, s[0:1]
	v_cndmask_b32_e64 v86, v20, 0, vcc
	v_cndmask_b32_e64 v87, v21, 0, vcc
	s_waitcnt vmcnt(0)
	v_pk_fma_f32 v[68:69], v[26:27], v[100:101], v[68:69]
	s_nop 0
	v_pk_fma_f32 v[68:69], v[96:97], v[74:75], v[68:69]
	v_mul_f32_e32 v74, 0xbfb8aa3b, v80
	v_exp_f32_e32 v74, v74
	v_pk_fma_f32 v[68:69], v[92:93], v[84:85], v[68:69]
	v_pk_fma_f32 v[70:71], v[28:29], v[102:103], v[70:71]
	v_add_f32_e32 v74, 1.0, v74
	v_rcp_f32_e32 v74, v74
	v_pk_fma_f32 v[70:71], v[98:99], v[86:87], v[70:71]
	v_mul_f32_e32 v74, v80, v74
	v_mul_f32_e32 v68, v68, v74
	v_mul_f32_e32 v74, 0xbfb8aa3b, v81
	v_exp_f32_e32 v74, v74
	v_pk_fma_f32 v[70:71], v[94:95], v[90:91], v[70:71]
	v_add_f32_e32 v74, 1.0, v74
	v_rcp_f32_e32 v74, v74
	s_nop 0
	v_mul_f32_e32 v74, v81, v74
	v_mul_f32_e32 v69, v69, v74
	v_mul_f32_e32 v74, 0xbfb8aa3b, v76
	v_exp_f32_e32 v74, v74
	v_cvt_pk_bf16_f32 v90, v68, v69
	v_and_b32_e32 v68, 64, v116
	v_cmp_ne_u32_e32 vcc, 0, v68
	v_add_f32_e32 v74, 1.0, v74
	v_rcp_f32_e32 v74, v74
	s_nop 0
	v_mul_f32_e32 v74, v76, v74
	v_mul_f32_e32 v70, v70, v74
	v_mul_f32_e32 v74, 0xbfb8aa3b, v77
	v_exp_f32_e32 v74, v74
	s_nop 0
	v_add_f32_e32 v74, 1.0, v74
	v_rcp_f32_e32 v74, v74
	s_nop 0
	v_mul_f32_e32 v74, v77, v74
	v_mul_f32_e32 v71, v71, v74
	v_cvt_pk_bf16_f32 v91, v70, v71
	s_and_saveexec_b64 s[0:1], vcc
	s_cbranch_execz .LBB0_1214
	v_add_u32_e32 v70, s17, v228
	v_mov_b64_e32 v[68:69], s[70:71]
	v_mad_i64_i32 v[68:69], s[38:39], v70, s34, v[68:69]
	s_lshl_b32 s38, s72, 7
	s_ashr_i32 s39, s38, 31
	v_lshl_add_u64 v[68:69], s[38:39], 1, v[68:69]
	v_lshlrev_b32_e32 v146, 1, v148
	v_lshl_add_u64 v[68:69], v[68:69], 0, v[146:147]
	global_store_dwordx4 v[68:69], v[88:91], off

.LBB0_1218:
	ds_read_b32 v124, v231
	s_waitcnt lgkmcnt(2)
	v_mov_b32_dpp v68, v14 row_shr:1 row_mask:0xf bank_mask:0xf
	v_mov_b32_dpp v69, v15 row_shr:1 row_mask:0xf bank_mask:0xf
	s_waitcnt lgkmcnt(1)
	v_mov_b32_dpp v84, v2 row_shr:1 row_mask:0xf bank_mask:0xf
	v_mov_b32_dpp v85, v3 row_shr:1 row_mask:0xf bank_mask:0xf
	s_waitcnt lgkmcnt(0)
	v_and_b32_e32 v80, 15, v124
	v_mul_u32_u24_e32 v80, 0x1600, v80
	v_lshlrev_b32_e32 v146, 2, v80
	v_lshl_add_u64 v[80:81], s[68:69], 0, v[146:147]
	v_and_b32_e32 v116, 16, v124
	v_lshl_add_u64 v[80:81], v[184:185], 2, v[80:81]
	v_cmp_eq_u32_e32 vcc, 0, v116
	v_and_b32_e32 v116, 32, v124
	v_cmp_eq_u32_e64 s[0:1], 0, v116
	global_load_dwordx4 v[116:119], v[80:81], off offset:16
	global_load_dwordx4 v[252:255], v[80:81], off offset:528
	v_cndmask_b32_e64 v120, v74, 0, vcc
	v_cndmask_b32_e64 v121, v75, 0, vcc
	v_cndmask_b32_e64 v122, v76, 0, vcc
	v_cndmask_b32_e64 v123, v77, 0, vcc
	v_cndmask_b32_e64 v88, v88, 0, s[0:1]
	v_cndmask_b32_e64 v89, v89, 0, s[0:1]
	v_cndmask_b32_e64 v90, v90, 0, s[0:1]
	v_cndmask_b32_e64 v91, v91, 0, s[0:1]
	v_cndmask_b32_e64 v84, v84, 0, s[0:1]
	v_cndmask_b32_e64 v85, v85, 0, s[0:1]
	v_mov_b32_dpp v70, v16 row_shr:1 row_mask:0xf bank_mask:0xf
	v_mov_b32_dpp v71, v17 row_shr:1 row_mask:0xf bank_mask:0xf
	v_mov_b32_dpp v86, v4 row_shr:1 row_mask:0xf bank_mask:0xf
	v_mov_b32_dpp v87, v5 row_shr:1 row_mask:0xf bank_mask:0xf
	v_cndmask_b32_e64 v86, v86, 0, s[0:1]
	v_cndmask_b32_e64 v87, v87, 0, s[0:1]
	s_waitcnt vmcnt(0)
	v_pk_fma_f32 v[118:119], v[166:167], v[114:115], v[118:119]
	v_pk_fma_f32 v[116:117], v[162:163], v[112:113], v[116:117]
	v_pk_fma_f32 v[118:119], v[110:111], v[122:123], v[118:119]
	v_pk_fma_f32 v[116:117], v[108:109], v[120:121], v[116:117]
	v_pk_fma_f32 v[118:119], v[106:107], v[90:91], v[118:119]
	v_pk_fma_f32 v[116:117], v[104:105], v[88:89], v[116:117]
	v_mov_b64_e32 v[88:89], v[252:253]
	v_mov_b64_e32 v[90:91], v[254:255]
	v_cndmask_b32_e64 v80, v68, 0, vcc
	v_cndmask_b32_e64 v81, v69, 0, vcc
	v_cndmask_b32_e64 v120, v70, 0, vcc
	v_cndmask_b32_e64 v121, v71, 0, vcc
	s_waitcnt vmcnt(0)
	v_pk_fma_f32 v[88:89], v[160:161], v[100:101], v[88:89]
	s_nop 0
	v_pk_fma_f32 v[80:81], v[96:97], v[80:81], v[88:89]
	v_pk_fma_f32 v[90:91], v[164:165], v[102:103], v[90:91]
	v_pk_fma_f32 v[80:81], v[92:93], v[84:85], v[80:81]
	v_mul_f32_e32 v84, 0xbfb8aa3b, v116
	v_exp_f32_e32 v84, v84
	v_mul_f32_e32 v85, 0xbfb8aa3b, v119
	v_exp_f32_e32 v85, v85
	v_pk_fma_f32 v[88:89], v[98:99], v[120:121], v[90:91]
	v_add_f32_e32 v84, 1.0, v84
	v_rcp_f32_e32 v84, v84
	v_add_f32_e32 v85, 1.0, v85
	v_rcp_f32_e32 v85, v85
	v_pk_fma_f32 v[86:87], v[94:95], v[86:87], v[88:89]
	v_mul_f32_e32 v84, v116, v84
	v_mul_f32_e32 v80, v80, v84
	v_mul_f32_e32 v84, 0xbfb8aa3b, v117
	v_exp_f32_e32 v84, v84
	v_mul_f32_e32 v85, v119, v85
	v_mul_f32_e32 v85, v87, v85
	v_add_f32_e32 v84, 1.0, v84
	v_rcp_f32_e32 v84, v84
	s_nop 0
	v_mul_f32_e32 v84, v117, v84
	v_mul_f32_e32 v81, v81, v84
	v_mul_f32_e32 v84, 0xbfb8aa3b, v118
	v_exp_f32_e32 v84, v84
	v_cvt_pk_bf16_f32 v80, v80, v81
	s_nop 0
	v_add_f32_e32 v84, 1.0, v84
	v_rcp_f32_e32 v84, v84
	s_nop 0
	v_mul_f32_e32 v84, v118, v84
	v_mul_f32_e32 v84, v86, v84
	v_cvt_pk_bf16_f32 v81, v84, v85
	v_and_b32_e32 v84, 64, v124
	v_cmp_ne_u32_e32 vcc, 0, v84
	s_and_saveexec_b64 s[0:1], vcc
	s_cbranch_execz .LBB0_1220
	v_add_u32_e32 v86, s17, v230
	v_mov_b64_e32 v[84:85], s[70:71]
	v_mad_i64_i32 v[84:85], s[38:39], v86, s34, v[84:85]
	s_lshl_b32 s38, s72, 7
	s_ashr_i32 s39, s38, 31
	v_lshl_add_u64 v[84:85], s[38:39], 1, v[84:85]
	v_lshlrev_b32_e32 v146, 1, v148
	v_lshl_add_u64 v[84:85], v[84:85], 0, v[146:147]
	global_store_dwordx4 v[84:85], v[78:81], off
.LBB0_1220:
	s_or_b64 exec, exec, s[0:1]
	ds_read_b32 v90, v233
	s_waitcnt lgkmcnt(0)
	v_and_b32_e32 v78, 15, v90
	v_mul_u32_u24_e32 v78, 0x1600, v78
	v_lshlrev_b32_e32 v146, 2, v78
	v_lshl_add_u64 v[78:79], s[68:69], 0, v[146:147]
	v_lshl_add_u64 v[84:85], v[184:185], 2, v[78:79]
	v_and_b32_e32 v78, 16, v90
	v_cmp_eq_u32_e32 vcc, 0, v78
	v_and_b32_e32 v78, 32, v90
	v_cmp_eq_u32_e64 s[0:1], 0, v78
	global_load_dwordx4 v[78:81], v[84:85], off offset:16
	global_load_dwordx4 v[252:255], v[84:85], off offset:528
	v_cndmask_b32_e64 v86, v162, 0, vcc
	v_cndmask_b32_e64 v87, v163, 0, vcc
	v_cndmask_b32_e64 v88, v166, 0, vcc
	v_cndmask_b32_e64 v89, v167, 0, vcc
	v_cndmask_b32_e64 v74, v74, 0, s[0:1]
	v_cndmask_b32_e64 v75, v75, 0, s[0:1]
	v_cndmask_b32_e64 v76, v76, 0, s[0:1]
	v_cndmask_b32_e64 v77, v77, 0, s[0:1]
	v_cndmask_b32_e64 v68, v68, 0, s[0:1]
	v_cndmask_b32_e64 v69, v69, 0, s[0:1]
	v_cndmask_b32_e64 v70, v70, 0, s[0:1]
	v_cndmask_b32_e64 v71, v71, 0, s[0:1]
	s_waitcnt vmcnt(0)
	v_pk_fma_f32 v[80:81], v[158:159], v[114:115], v[80:81]
	v_pk_fma_f32 v[78:79], v[136:137], v[112:113], v[78:79]
	v_pk_fma_f32 v[80:81], v[110:111], v[88:89], v[80:81]
	v_pk_fma_f32 v[78:79], v[108:109], v[86:87], v[78:79]
	v_pk_fma_f32 v[80:81], v[106:107], v[76:77], v[80:81]
	v_pk_fma_f32 v[78:79], v[104:105], v[74:75], v[78:79]
	v_mov_b64_e32 v[74:75], v[252:253]
	v_mov_b64_e32 v[76:77], v[254:255]
	v_cndmask_b32_e64 v84, v160, 0, vcc
	v_cndmask_b32_e64 v85, v161, 0, vcc
	v_cndmask_b32_e64 v86, v164, 0, vcc
	v_cndmask_b32_e64 v87, v165, 0, vcc
	s_waitcnt vmcnt(0)
	v_pk_fma_f32 v[74:75], v[132:133], v[100:101], v[74:75]
	s_nop 0
	v_pk_fma_f32 v[74:75], v[96:97], v[84:85], v[74:75]
	v_pk_fma_f32 v[76:77], v[134:135], v[102:103], v[76:77]
	v_pk_fma_f32 v[68:69], v[92:93], v[68:69], v[74:75]
	v_mul_f32_e32 v74, 0xbfb8aa3b, v78
	v_exp_f32_e32 v74, v74
	v_pk_fma_f32 v[76:77], v[98:99], v[86:87], v[76:77]
	v_add_f32_e32 v74, 1.0, v74
	v_rcp_f32_e32 v74, v74
	v_pk_fma_f32 v[70:71], v[94:95], v[70:71], v[76:77]
	v_mul_f32_e32 v74, v78, v74
	v_mul_f32_e32 v68, v68, v74
	v_mul_f32_e32 v74, 0xbfb8aa3b, v79
	v_exp_f32_e32 v74, v74
	s_nop 0
	v_add_f32_e32 v74, 1.0, v74
	v_rcp_f32_e32 v74, v74
	s_nop 0
	v_mul_f32_e32 v74, v79, v74
	v_mul_f32_e32 v69, v69, v74
	v_mul_f32_e32 v74, 0xbfb8aa3b, v80
	v_exp_f32_e32 v74, v74
	s_nop 0
	v_add_f32_e32 v74, 1.0, v74
	v_rcp_f32_e32 v74, v74
	s_nop 0
	v_mul_f32_e32 v74, v80, v74
	v_mul_f32_e32 v70, v70, v74
	v_mul_f32_e32 v74, 0xbfb8aa3b, v81
	v_exp_f32_e32 v74, v74
	s_nop 0
	v_add_f32_e32 v74, 1.0, v74
	v_rcp_f32_e32 v74, v74
	s_nop 0
	v_mul_f32_e32 v74, v81, v74
	v_mul_f32_e32 v71, v71, v74
	v_cvt_pk_bf16_f32 v74, v68, v69
	v_and_b32_e32 v68, 64, v90
	v_cmp_ne_u32_e32 vcc, 0, v68
	v_cvt_pk_bf16_f32 v75, v70, v71
	s_and_saveexec_b64 s[0:1], vcc
	s_cbranch_execz .LBB0_1222
	v_add_u32_e32 v70, s17, v232
	v_mov_b64_e32 v[68:69], s[70:71]
	v_mad_i64_i32 v[68:69], s[38:39], v70, s34, v[68:69]
	s_lshl_b32 s38, s72, 7
	s_ashr_i32 s39, s38, 31
	v_lshl_add_u64 v[68:69], s[38:39], 1, v[68:69]
	v_lshlrev_b32_e32 v146, 1, v148
	v_lshl_add_u64 v[68:69], v[68:69], 0, v[146:147]
	global_store_dwordx4 v[68:69], v[72:75], off
.LBB0_1222:
	s_or_b64 exec, exec, s[0:1]
	ds_read_b32 v86, v235
	s_waitcnt lgkmcnt(0)
	v_and_b32_e32 v68, 15, v86
	v_mul_u32_u24_e32 v68, 0x1600, v68
	v_lshlrev_b32_e32 v146, 2, v68
	v_lshl_add_u64 v[68:69], s[68:69], 0, v[146:147]
	v_lshl_add_u64 v[72:73], v[184:185], 2, v[68:69]
	v_and_b32_e32 v68, 16, v86
	v_cmp_eq_u32_e32 vcc, 0, v68
	v_and_b32_e32 v68, 32, v86
	v_cmp_eq_u32_e64 s[0:1], 0, v68
	global_load_dwordx4 v[68:71], v[72:73], off offset:16
	global_load_dwordx4 v[252:255], v[72:73], off offset:528
	v_cndmask_b32_e64 v74, v136, 0, vcc
	v_cndmask_b32_e64 v75, v137, 0, vcc
	v_cndmask_b32_e64 v78, v158, 0, vcc
	v_cndmask_b32_e64 v79, v159, 0, vcc
	v_cndmask_b32_e64 v76, v162, 0, s[0:1]
	v_cndmask_b32_e64 v77, v163, 0, s[0:1]
	v_cndmask_b32_e64 v80, v166, 0, s[0:1]
	v_cndmask_b32_e64 v81, v167, 0, s[0:1]
	v_cndmask_b32_e64 v84, v164, 0, s[0:1]
	v_cndmask_b32_e64 v85, v165, 0, s[0:1]
	s_waitcnt vmcnt(0)
	v_pk_fma_f32 v[70:71], v[8:9], v[114:115], v[70:71]
	v_pk_fma_f32 v[68:69], v[6:7], v[112:113], v[68:69]
	v_pk_fma_f32 v[70:71], v[110:111], v[78:79], v[70:71]
	v_pk_fma_f32 v[68:69], v[108:109], v[74:75], v[68:69]
	v_pk_fma_f32 v[74:75], v[106:107], v[80:81], v[70:71]
	v_pk_fma_f32 v[76:77], v[104:105], v[76:77], v[68:69]
	v_mov_b64_e32 v[68:69], v[252:253]
	v_mov_b64_e32 v[70:71], v[254:255]
	v_cndmask_b32_e64 v72, v132, 0, vcc
	v_cndmask_b32_e64 v73, v133, 0, vcc
	v_cndmask_b32_e64 v78, v160, 0, s[0:1]
	v_cndmask_b32_e64 v79, v161, 0, s[0:1]
	v_cndmask_b32_e64 v80, v134, 0, vcc
	v_cndmask_b32_e64 v81, v135, 0, vcc
	s_waitcnt vmcnt(0)
	v_pk_fma_f32 v[68:69], v[2:3], v[100:101], v[68:69]
	s_nop 0
	v_pk_fma_f32 v[68:69], v[96:97], v[72:73], v[68:69]
	v_mul_f32_e32 v72, 0xbfb8aa3b, v76
	v_exp_f32_e32 v72, v72
	v_pk_fma_f32 v[68:69], v[92:93], v[78:79], v[68:69]
	v_pk_fma_f32 v[70:71], v[4:5], v[102:103], v[70:71]
	v_add_f32_e32 v72, 1.0, v72
	v_rcp_f32_e32 v72, v72
	v_pk_fma_f32 v[70:71], v[98:99], v[80:81], v[70:71]
	v_mul_f32_e32 v72, v76, v72
	v_mul_f32_e32 v68, v68, v72
	v_mul_f32_e32 v72, 0xbfb8aa3b, v77
	v_exp_f32_e32 v72, v72
	v_pk_fma_f32 v[70:71], v[94:95], v[84:85], v[70:71]
	v_add_f32_e32 v72, 1.0, v72
	v_rcp_f32_e32 v72, v72
	s_nop 0
	v_mul_f32_e32 v72, v77, v72
	v_mul_f32_e32 v69, v69, v72
	v_mul_f32_e32 v72, 0xbfb8aa3b, v74
	v_exp_f32_e32 v72, v72
	v_cvt_pk_bf16_f32 v68, v68, v69
	s_nop 0
	v_add_f32_e32 v72, 1.0, v72
	v_rcp_f32_e32 v72, v72
	s_nop 0
	v_mul_f32_e32 v72, v74, v72
	v_mul_f32_e32 v70, v70, v72
	v_mul_f32_e32 v72, 0xbfb8aa3b, v75
	v_exp_f32_e32 v72, v72
	s_nop 0
	v_add_f32_e32 v72, 1.0, v72
	v_rcp_f32_e32 v72, v72
	s_nop 0
	v_mul_f32_e32 v72, v75, v72
	v_mul_f32_e32 v71, v71, v72
	v_cvt_pk_bf16_f32 v69, v70, v71
	v_and_b32_e32 v70, 64, v86
	v_cmp_ne_u32_e32 vcc, 0, v70
	s_and_saveexec_b64 s[0:1], vcc
	s_cbranch_execz .LBB0_1224
	v_add_u32_e32 v72, s17, v234
	v_mov_b64_e32 v[70:71], s[70:71]
	v_mad_i64_i32 v[70:71], s[38:39], v72, s34, v[70:71]
	s_lshl_b32 s38, s72, 7
	s_ashr_i32 s39, s38, 31
	v_lshl_add_u64 v[70:71], s[38:39], 1, v[70:71]
	v_lshlrev_b32_e32 v146, 1, v148
	v_lshl_add_u64 v[70:71], v[70:71], 0, v[146:147]
	global_store_dwordx4 v[70:71], v[66:69], off
.LBB0_1224:
	s_or_b64 exec, exec, s[0:1]
	ds_read_b32 v86, v237
	s_waitcnt lgkmcnt(0)
	v_and_b32_e32 v66, 15, v86
	v_mul_u32_u24_e32 v66, 0x1600, v66
	v_lshlrev_b32_e32 v146, 2, v66
	v_lshl_add_u64 v[66:67], s[68:69], 0, v[146:147]
	v_lshl_add_u64 v[70:71], v[184:185], 2, v[66:67]
	v_and_b32_e32 v66, 16, v86
	v_cmp_eq_u32_e32 vcc, 0, v66
	v_and_b32_e32 v66, 32, v86
	v_cmp_eq_u32_e64 s[0:1], 0, v66
	global_load_dwordx4 v[66:69], v[70:71], off offset:16
	global_load_dwordx4 v[252:255], v[70:71], off offset:528
	v_cndmask_b32_e64 v72, v6, 0, vcc
	v_cndmask_b32_e64 v73, v7, 0, vcc
	v_cndmask_b32_e64 v76, v8, 0, vcc
	v_cndmask_b32_e64 v77, v9, 0, vcc
	v_cndmask_b32_e64 v74, v136, 0, s[0:1]
	v_cndmask_b32_e64 v75, v137, 0, s[0:1]
	v_cndmask_b32_e64 v78, v158, 0, s[0:1]
	v_cndmask_b32_e64 v79, v159, 0, s[0:1]
	v_cndmask_b32_e64 v80, v134, 0, s[0:1]
	v_cndmask_b32_e64 v81, v135, 0, s[0:1]
	s_waitcnt vmcnt(0)
	v_pk_fma_f32 v[68:69], v[12:13], v[114:115], v[68:69]
	v_pk_fma_f32 v[66:67], v[10:11], v[112:113], v[66:67]
	v_pk_fma_f32 v[68:69], v[110:111], v[76:77], v[68:69]
	v_pk_fma_f32 v[66:67], v[108:109], v[72:73], v[66:67]
	v_pk_fma_f32 v[72:73], v[106:107], v[78:79], v[68:69]
	v_pk_fma_f32 v[74:75], v[104:105], v[74:75], v[66:67]
	v_mov_b64_e32 v[66:67], v[252:253]
	v_mov_b64_e32 v[68:69], v[254:255]
	v_cndmask_b32_e64 v70, v2, 0, vcc
	v_cndmask_b32_e64 v71, v3, 0, vcc
	v_cndmask_b32_e64 v76, v132, 0, s[0:1]
	v_cndmask_b32_e64 v77, v133, 0, s[0:1]
	v_cndmask_b32_e64 v78, v4, 0, vcc
	v_cndmask_b32_e64 v79, v5, 0, vcc
	s_waitcnt vmcnt(0)
	v_pk_fma_f32 v[66:67], v[14:15], v[100:101], v[66:67]
	s_nop 0
	v_pk_fma_f32 v[66:67], v[96:97], v[70:71], v[66:67]
	v_mul_f32_e32 v70, 0xbfb8aa3b, v74
	v_exp_f32_e32 v70, v70
	v_pk_fma_f32 v[66:67], v[92:93], v[76:77], v[66:67]
	v_pk_fma_f32 v[68:69], v[16:17], v[102:103], v[68:69]
	v_add_f32_e32 v70, 1.0, v70
	v_rcp_f32_e32 v70, v70
	v_pk_fma_f32 v[68:69], v[98:99], v[78:79], v[68:69]
	v_mul_f32_e32 v70, v74, v70
	v_mul_f32_e32 v66, v66, v70
	v_mul_f32_e32 v70, 0xbfb8aa3b, v75
	v_exp_f32_e32 v70, v70
	v_pk_fma_f32 v[68:69], v[94:95], v[80:81], v[68:69]
	v_add_f32_e32 v70, 1.0, v70
	v_rcp_f32_e32 v70, v70
	s_nop 0
	v_mul_f32_e32 v70, v75, v70
	v_mul_f32_e32 v67, v67, v70
	v_mul_f32_e32 v70, 0xbfb8aa3b, v72
	v_exp_f32_e32 v70, v70
	v_cvt_pk_bf16_f32 v84, v66, v67
	v_and_b32_e32 v66, 64, v86
	v_cmp_ne_u32_e32 vcc, 0, v66
	v_add_f32_e32 v70, 1.0, v70
	v_rcp_f32_e32 v70, v70
	s_nop 0
	v_mul_f32_e32 v70, v72, v70
	v_mul_f32_e32 v68, v68, v70
	v_mul_f32_e32 v70, 0xbfb8aa3b, v73
	v_exp_f32_e32 v70, v70
	s_nop 0
	v_add_f32_e32 v70, 1.0, v70
	v_rcp_f32_e32 v70, v70
	s_nop 0
	v_mul_f32_e32 v70, v73, v70
	v_mul_f32_e32 v69, v69, v70
	v_cvt_pk_bf16_f32 v85, v68, v69
	s_and_saveexec_b64 s[0:1], vcc
	s_cbranch_execz .LBB0_1226
	v_add_u32_e32 v68, s17, v236
	v_mov_b64_e32 v[66:67], s[70:71]
	v_mad_i64_i32 v[66:67], s[38:39], v68, s34, v[66:67]
	s_lshl_b32 s38, s72, 7
	s_ashr_i32 s39, s38, 31
	v_lshl_add_u64 v[66:67], s[38:39], 1, v[66:67]
	v_lshlrev_b32_e32 v146, 1, v148
	v_lshl_add_u64 v[66:67], v[66:67], 0, v[146:147]
	global_store_dwordx4 v[66:67], v[82:85], off
